# attention loop v6 with the two K LDS-DMA issues moved into the otherwise empty QK gaps 8 and 9 (m0 write one MFMA earlier, no s_nop)
# baseline (speedup 1.0000x reference)
; __device__ __forceinline__ void qkt(f32x16& p0, f32x16& p1, const bf16* Ks, const bf16x8* qr, int r32, int hi) {
;   p0 = f32x16{}; p1 = f32x16{};
; #pragma unroll
;   for (int d0 = 0; d0 < 8; ++d0) { int cb = (d0 * 16 + hi * 8) * 2;
;     bf16x8 b0 = *reinterpret_cast<const bf16x8*>((const char*)Ks + KSWZ(r32, cb));
;     bf16x8 b1 = *reinterpret_cast<const bf16x8*>((const char*)Ks + KSWZ(32 + r32, cb));
;     p0 = __builtin_amdgcn_mfma_f32_32x32x16_bf16(b0, qr[d0], p0, 0, 0, 0);
;     p1 = __builtin_amdgcn_mfma_f32_32x32x16_bf16(b1, qr[d0], p1, 0, 0, 0); }
; }
; __device__ __forceinline__ int v_st(int k, int c) { const int kk = (k & ~0xC) | ((k & 4) << 1) | ((k & 8) >> 1); return ((kk >> 3) * 4 + (c >> 5)) * 512 + ((kk & 7) * 32 + (c & 31)) * 2; }
; __device__ __forceinline__ int v_rd_base(int lane) { return ((lane & 3) << 3) | (((lane >> 2) & 3) << 6) | (((lane >> 4) & 1) << 5) | (((lane >> 5) & 1) << 8); }
; template <int OFF> __device__ __forceinline__ s16x4 tr_read(int vb) {
;   s16x4 r; asm volatile("ds_read_b64_tr_b16 %0, %1 offset:%2" : "=&v"(r) : "v"(vb), "i"(OFF) : "memory"); return r;
; }
; template <int D0> __device__ __forceinline__ void pv_one(f32x16& od, int vb, bf16x8 pa0, bf16x8 pa1, bf16x8 pa2, bf16x8 pa3) {
;   const s16x4 l0 = tr_read<v_rd_off(D0, 0, 0)>(vb), h0 = tr_read<v_rd_off(D0, 0, 1)>(vb), l1 = tr_read<v_rd_off(D0, 1, 0)>(vb), h1 = tr_read<v_rd_off(D0, 1, 1)>(vb);
;   const s16x4 l2 = tr_read<v_rd_off(D0, 2, 0)>(vb), h2 = tr_read<v_rd_off(D0, 2, 1)>(vb), l3 = tr_read<v_rd_off(D0, 3, 0)>(vb), h3 = tr_read<v_rd_off(D0, 3, 1)>(vb);
;   asm volatile("s_waitcnt lgkmcnt(0)" ::: "memory"); SBAR();
;     ...
;   od = __builtin_amdgcn_mfma_f32_32x32x16_bf16(pa0, PK(l0, h0), od, 0, 0, 0);
;   od = __builtin_amdgcn_mfma_f32_32x32x16_bf16(pa1, PK(l1, h1), od, 0, 0, 0);
;   od = __builtin_amdgcn_mfma_f32_32x32x16_bf16(pa2, PK(l2, h2), od, 0, 0, 0);
;   od = __builtin_amdgcn_mfma_f32_32x32x16_bf16(pa3, PK(l3, h3), od, 0, 0, 0);
;     ...
; }
; __device__ __forceinline__ void partialSM_fast(f32x16& p0, f32x16& p1) {
; #pragma unroll
;   for (int r = 0; r < 16; ++r) p0[r] = __builtin_amdgcn_exp2f(p0[r]);
; }
; __device__ __forceinline__ void finishSM_fast(f32x16& p0, f32x16& p1, float& l_reg, bf16x8& pa0, bf16x8& pa1, bf16x8& pa2, bf16x8& pa3) {
; #pragma unroll
;   for (int r = 0; r < 16; ++r) p1[r] = __builtin_amdgcn_exp2f(p1[r]);
;   float ps = 0;
.Lattn_loop:
	s_waitcnt lgkmcnt(4)
	v_mfma_f32_32x32x16_bf16 v[96:111], v[206:209], v[112:115], 0
	ds_read_b128 v[206:209], v194 offset:24576
	v_cvt_pk_bf16_f32 v152, v64, v65
	v_cvt_pk_bf16_f32 v153, v66, v67
	v_add_f32_e32 v239, v64, v65
	v_add_f32_e32 v239, v66, v239
	v_mfma_f32_32x32x16_bf16 v[96:111], v[210:213], v[116:119], v[96:111]
	ds_read_b128 v[210:213], v196 offset:24576
	v_cvt_pk_bf16_f32 v154, v68, v69
	v_cvt_pk_bf16_f32 v155, v70, v71
	v_add_f32_e32 v239, v67, v239
	v_add_f32_e32 v239, v68, v239
	v_mfma_f32_32x32x16_bf16 v[96:111], v[214:217], v[120:123], v[96:111]
	ds_read_b128 v[214:217], v198 offset:24576
	v_add_f32_e32 v239, v69, v239
	v_add_f32_e32 v239, v70, v239
	v_mfma_f32_32x32x16_bf16 v[96:111], v[218:221], v[124:127], v[96:111]
	ds_read_b128 v[218:221], v199 offset:24576
	v_add_f32_e32 v239, v71, v239
	v_add_f32_e32 v239, v72, v239
	s_waitcnt lgkmcnt(4)
	v_mfma_f32_32x32x16_bf16 v[96:111], v[160:163], v[128:131], v[96:111]
	ds_read_b128 v[160:163], v200 offset:24576
	v_cvt_pk_bf16_f32 v156, v72, v73
	v_cvt_pk_bf16_f32 v157, v74, v75
	v_add_f32_e32 v239, v73, v239
	v_add_f32_e32 v239, v74, v239
	v_mfma_f32_32x32x16_bf16 v[96:111], v[164:167], v[132:135], v[96:111]
	ds_read_b128 v[164:167], v201 offset:24576
	v_cvt_pk_bf16_f32 v158, v76, v77
	v_cvt_pk_bf16_f32 v159, v78, v79
	v_add_f32_e32 v239, v75, v239
	v_add_f32_e32 v239, v76, v239
	v_mfma_f32_32x32x16_bf16 v[96:111], v[168:171], v[136:139], v[96:111]
	ds_read_b128 v[168:171], v202 offset:24576
	v_add_f32_e32 v239, v77, v239
	v_add_f32_e32 v239, v78, v239
	v_mfma_f32_32x32x16_bf16 v[96:111], v[172:175], v[148:151], v[96:111]
	ds_read_b128 v[172:175], v203 offset:24576
	v_add_f32_e32 v239, v79, v239
	v_add_f32_e32 v197, v239, v197
	s_add_u32 m0, s5, 0x10800
	s_waitcnt lgkmcnt(4)
	v_mfma_f32_32x32x16_bf16 v[64:79], v[206:209], v[112:115], 0
	global_load_lds_dwordx4 v244, s[0:1]
	s_add_u32 m0, s5, 0x12800
	v_mfma_f32_32x32x16_bf16 v[64:79], v[210:213], v[116:119], v[64:79]
	global_load_lds_dwordx4 v245, s[0:1]
	v_mfma_f32_32x32x16_bf16 v[64:79], v[214:217], v[120:123], v[64:79]
	ds_read_b64_tr_b16 v[222:223], v188
	ds_read_b64_tr_b16 v[224:225], v188 offset:2048
	v_mfma_f32_32x32x16_bf16 v[64:79], v[218:221], v[124:127], v[64:79]
	ds_read_b64_tr_b16 v[226:227], v188 offset:512
	ds_read_b64_tr_b16 v[228:229], v188 offset:2560
	v_exp_f32_e32 v96, v96
	v_exp_f32_e32 v97, v97
	s_waitcnt lgkmcnt(4)
	v_mfma_f32_32x32x16_bf16 v[64:79], v[160:163], v[128:131], v[64:79]
	ds_read_b64_tr_b16 v[230:231], v188 offset:1024
	ds_read_b64_tr_b16 v[232:233], v188 offset:3072
	v_exp_f32_e32 v98, v98
	v_exp_f32_e32 v99, v99
	v_exp_f32_e32 v100, v100
	v_mfma_f32_32x32x16_bf16 v[64:79], v[164:167], v[132:135], v[64:79]
	ds_read_b64_tr_b16 v[234:235], v188 offset:1536
	ds_read_b64_tr_b16 v[236:237], v188 offset:3584
	v_exp_f32_e32 v101, v101
	v_exp_f32_e32 v102, v102
	v_exp_f32_e32 v103, v103
	v_mfma_f32_32x32x16_bf16 v[64:79], v[168:171], v[136:139], v[64:79]
	ds_read_b64_tr_b16 v[240:241], v188 offset:4096
	ds_read_b64_tr_b16 v[242:243], v188 offset:6144
	v_exp_f32_e32 v104, v104
	v_exp_f32_e32 v105, v105
	v_mfma_f32_32x32x16_bf16 v[64:79], v[172:175], v[148:151], v[64:79]
	ds_read_b64_tr_b16 v[180:181], v188 offset:4608
	ds_read_b64_tr_b16 v[182:183], v188 offset:6656
	v_exp_f32_e32 v106, v106
	v_exp_f32_e32 v107, v107
	s_waitcnt lgkmcnt(6)
	v_mfma_f32_32x32x16_bf16 v[0:15], v[140:143], v[222:225], v[0:15]
	ds_read_b64_tr_b16 v[222:223], v188 offset:5120
	ds_read_b64_tr_b16 v[224:225], v188 offset:7168
	v_exp_f32_e32 v108, v108
	v_exp_f32_e32 v109, v109
	v_mfma_f32_32x32x16_bf16 v[16:31], v[140:143], v[226:229], v[16:31]
	ds_read_b64_tr_b16 v[226:227], v188 offset:5632
	ds_read_b64_tr_b16 v[228:229], v188 offset:7680
	v_exp_f32_e32 v110, v110
	v_exp_f32_e32 v111, v111
	v_mfma_f32_32x32x16_bf16 v[32:47], v[140:143], v[230:233], v[32:47]
	ds_read_b64_tr_b16 v[230:231], v188 offset:8192
	ds_read_b64_tr_b16 v[232:233], v188 offset:10240
	v_exp_f32_e32 v64, v64
	v_exp_f32_e32 v65, v65
	s_waitcnt lgkmcnt(6)
	v_mfma_f32_32x32x16_bf16 v[48:63], v[140:143], v[234:237], v[48:63]
	ds_read_b64_tr_b16 v[234:235], v188 offset:8704
	ds_read_b64_tr_b16 v[236:237], v188 offset:10752
	v_exp_f32_e32 v66, v66
	v_exp_f32_e32 v67, v67
	v_mfma_f32_32x32x16_bf16 v[0:15], v[144:147], v[240:243], v[0:15]
	ds_read_b64_tr_b16 v[240:241], v188 offset:9216
	ds_read_b64_tr_b16 v[242:243], v188 offset:11264
	v_exp_f32_e32 v68, v68
	v_exp_f32_e32 v69, v69
	v_cvt_pk_bf16_f32 v140, v96, v97
	v_cvt_pk_bf16_f32 v141, v98, v99
	v_mfma_f32_32x32x16_bf16 v[16:31], v[144:147], v[180:183], v[16:31]
	ds_read_b64_tr_b16 v[180:181], v188 offset:9728
	ds_read_b64_tr_b16 v[182:183], v188 offset:11776
	v_exp_f32_e32 v70, v70
	v_exp_f32_e32 v71, v71
	v_cvt_pk_bf16_f32 v142, v100, v101
	v_cvt_pk_bf16_f32 v143, v102, v103
	s_waitcnt lgkmcnt(6)
	v_mfma_f32_32x32x16_bf16 v[32:47], v[144:147], v[222:225], v[32:47]
	ds_read_b64_tr_b16 v[222:223], v188 offset:12288
	ds_read_b64_tr_b16 v[224:225], v188 offset:14336
	v_exp_f32_e32 v72, v72
	v_exp_f32_e32 v73, v73
	v_mfma_f32_32x32x16_bf16 v[48:63], v[144:147], v[226:229], v[48:63]
	ds_read_b64_tr_b16 v[226:227], v188 offset:12800
	ds_read_b64_tr_b16 v[228:229], v188 offset:14848
	v_exp_f32_e32 v74, v74
	v_exp_f32_e32 v75, v75
	v_mfma_f32_32x32x16_bf16 v[0:15], v[152:155], v[230:233], v[0:15]
	ds_read_b64_tr_b16 v[230:231], v188 offset:13312
	ds_read_b64_tr_b16 v[232:233], v188 offset:15360
	v_exp_f32_e32 v76, v76
	v_exp_f32_e32 v77, v77
	v_cvt_pk_bf16_f32 v144, v104, v105
	v_cvt_pk_bf16_f32 v145, v106, v107
	s_waitcnt lgkmcnt(6)
	v_mfma_f32_32x32x16_bf16 v[16:31], v[152:155], v[234:237], v[16:31]
	ds_read_b64_tr_b16 v[234:235], v188 offset:13824
	ds_read_b64_tr_b16 v[236:237], v188 offset:15872
	v_exp_f32_e32 v78, v78
	v_exp_f32_e32 v79, v79
	v_cvt_pk_bf16_f32 v146, v108, v109
	v_cvt_pk_bf16_f32 v147, v110, v111
	s_waitcnt vmcnt(6)
	s_barrier
; __device__ __forceinline__ void qkt(f32x16& p0, f32x16& p1, const bf16* Ks, const bf16x8* qr, int r32, int hi) {
;   p0 = f32x16{}; p1 = f32x16{};
; #pragma unroll
;   for (int d0 = 0; d0 < 8; ++d0) { int cb = (d0 * 16 + hi * 8) * 2;
;     bf16x8 b0 = *reinterpret_cast<const bf16x8*>((const char*)Ks + KSWZ(r32, cb));
;     bf16x8 b1 = *reinterpret_cast<const bf16x8*>((const char*)Ks + KSWZ(32 + r32, cb));
;     p0 = __builtin_amdgcn_mfma_f32_32x32x16_bf16(b0, qr[d0], p0, 0, 0, 0);
;     p1 = __builtin_amdgcn_mfma_f32_32x32x16_bf16(b1, qr[d0], p1, 0, 0, 0); }
; }
; __device__ __forceinline__ int v_st(int k, int c) { const int kk = (k & ~0xC) | ((k & 4) << 1) | ((k & 8) >> 1); return ((kk >> 3) * 4 + (c >> 5)) * 512 + ((kk & 7) * 32 + (c & 31)) * 2; }
; __device__ __forceinline__ int v_rd_base(int lane) { return ((lane & 3) << 3) | (((lane >> 2) & 3) << 6) | (((lane >> 4) & 1) << 5) | (((lane >> 5) & 1) << 8); }
; template <int OFF> __device__ __forceinline__ s16x4 tr_read(int vb) {
;   s16x4 r; asm volatile("ds_read_b64_tr_b16 %0, %1 offset:%2" : "=&v"(r) : "v"(vb), "i"(OFF) : "memory"); return r;
; }
; template <int D0> __device__ __forceinline__ void pv_one(f32x16& od, int vb, bf16x8 pa0, bf16x8 pa1, bf16x8 pa2, bf16x8 pa3) {
;   const s16x4 l0 = tr_read<v_rd_off(D0, 0, 0)>(vb), h0 = tr_read<v_rd_off(D0, 0, 1)>(vb), l1 = tr_read<v_rd_off(D0, 1, 0)>(vb), h1 = tr_read<v_rd_off(D0, 1, 1)>(vb);
;   const s16x4 l2 = tr_read<v_rd_off(D0, 2, 0)>(vb), h2 = tr_read<v_rd_off(D0, 2, 1)>(vb), l3 = tr_read<v_rd_off(D0, 3, 0)>(vb), h3 = tr_read<v_rd_off(D0, 3, 1)>(vb);
;   asm volatile("s_waitcnt lgkmcnt(0)" ::: "memory"); SBAR();
;     ...
;   od = __builtin_amdgcn_mfma_f32_32x32x16_bf16(pa0, PK(l0, h0), od, 0, 0, 0);
;   od = __builtin_amdgcn_mfma_f32_32x32x16_bf16(pa1, PK(l1, h1), od, 0, 0, 0);
;   od = __builtin_amdgcn_mfma_f32_32x32x16_bf16(pa2, PK(l2, h2), od, 0, 0, 0);
;   od = __builtin_amdgcn_mfma_f32_32x32x16_bf16(pa3, PK(l3, h3), od, 0, 0, 0);
;     ...
; }
; __device__ __forceinline__ void partialSM_fast(f32x16& p0, f32x16& p1) {
; #pragma unroll
;   for (int r = 0; r < 16; ++r) p0[r] = __builtin_amdgcn_exp2f(p0[r]);
; }
; __device__ __forceinline__ void finishSM_fast(f32x16& p0, f32x16& p1, float& l_reg, bf16x8& pa0, bf16x8& pa1, bf16x8& pa2, bf16x8& pa3) {
; #pragma unroll
;   for (int r = 0; r < 16; ++r) p1[r] = __builtin_amdgcn_exp2f(p1[r]);
;   float ps = 0;
	v_mfma_f32_32x32x16_bf16 v[32:47], v[152:155], v[240:243], v[32:47]
	s_add_u32 m0, s5, 0xc000
	v_add_f32_e32 v238, v96, v97
	global_load_lds_dwordx4 v253, s[0:1]
	v_add_f32_e32 v238, v98, v238
	v_add_f32_e32 v238, v99, v238
	v_mfma_f32_32x32x16_bf16 v[48:63], v[152:155], v[180:183], v[48:63]
	s_add_u32 m0, s5, 0xe000
	v_add_f32_e32 v238, v100, v238
	global_load_lds_dwordx4 v254, s[0:1]
	v_add_f32_e32 v238, v101, v238
	v_add_f32_e32 v238, v102, v238
	s_add_u32 s0, s0, 0x4000
	s_addc_u32 s1, s1, 0
	s_waitcnt lgkmcnt(2)
	v_mfma_f32_32x32x16_bf16 v[0:15], v[156:159], v[222:225], v[0:15]
	v_add_f32_e32 v238, v103, v238
	v_add_f32_e32 v238, v104, v238
	v_add_f32_e32 v238, v105, v238
	ds_read_b128 v[206:209], v194 offset:32768
	ds_read_b128 v[210:213], v196 offset:32768
	v_mfma_f32_32x32x16_bf16 v[16:31], v[156:159], v[226:229], v[16:31]
	v_add_f32_e32 v238, v106, v238
	v_add_f32_e32 v238, v107, v238
	v_add_f32_e32 v238, v108, v238
	ds_read_b128 v[214:217], v198 offset:32768
	ds_read_b128 v[218:221], v199 offset:32768
	v_mfma_f32_32x32x16_bf16 v[32:47], v[156:159], v[230:233], v[32:47]
	v_add_f32_e32 v238, v109, v238
	v_add_f32_e32 v238, v110, v238
	ds_read_b128 v[160:163], v200 offset:32768
	ds_read_b128 v[164:167], v201 offset:32768
	s_waitcnt lgkmcnt(6)
	v_mfma_f32_32x32x16_bf16 v[48:63], v[156:159], v[234:237], v[48:63]
	v_add_f32_e32 v238, v111, v238
	v_add_f32_e32 v197, v238, v197
	ds_read_b128 v[168:171], v202 offset:32768
	ds_read_b128 v[172:175], v203 offset:32768
	s_waitcnt lgkmcnt(4)
	v_mfma_f32_32x32x16_bf16 v[96:111], v[206:209], v[112:115], 0
	ds_read_b128 v[206:209], v194 offset:40960
	v_cvt_pk_bf16_f32 v152, v64, v65
	v_cvt_pk_bf16_f32 v153, v66, v67
	v_add_f32_e32 v239, v64, v65
	v_add_f32_e32 v239, v66, v239
	v_mfma_f32_32x32x16_bf16 v[96:111], v[210:213], v[116:119], v[96:111]
	ds_read_b128 v[210:213], v196 offset:40960
	v_cvt_pk_bf16_f32 v154, v68, v69
	v_cvt_pk_bf16_f32 v155, v70, v71
	v_add_f32_e32 v239, v67, v239
	v_add_f32_e32 v239, v68, v239
	v_mfma_f32_32x32x16_bf16 v[96:111], v[214:217], v[120:123], v[96:111]
	ds_read_b128 v[214:217], v198 offset:40960
	v_add_f32_e32 v239, v69, v239
	v_add_f32_e32 v239, v70, v239
	v_mfma_f32_32x32x16_bf16 v[96:111], v[218:221], v[124:127], v[96:111]
	ds_read_b128 v[218:221], v199 offset:40960
	v_add_f32_e32 v239, v71, v239
	v_add_f32_e32 v239, v72, v239
	s_waitcnt lgkmcnt(4)
	v_mfma_f32_32x32x16_bf16 v[96:111], v[160:163], v[128:131], v[96:111]
	ds_read_b128 v[160:163], v200 offset:40960
	v_cvt_pk_bf16_f32 v156, v72, v73
	v_cvt_pk_bf16_f32 v157, v74, v75
	v_add_f32_e32 v239, v73, v239
	v_add_f32_e32 v239, v74, v239
	v_mfma_f32_32x32x16_bf16 v[96:111], v[164:167], v[132:135], v[96:111]
	ds_read_b128 v[164:167], v201 offset:40960
	v_cvt_pk_bf16_f32 v158, v76, v77
	v_cvt_pk_bf16_f32 v159, v78, v79
	v_add_f32_e32 v239, v75, v239
	v_add_f32_e32 v239, v76, v239
	v_mfma_f32_32x32x16_bf16 v[96:111], v[168:171], v[136:139], v[96:111]
	ds_read_b128 v[168:171], v202 offset:40960
	v_add_f32_e32 v239, v77, v239
	v_add_f32_e32 v239, v78, v239
	v_mfma_f32_32x32x16_bf16 v[96:111], v[172:175], v[148:151], v[96:111]
	ds_read_b128 v[172:175], v203 offset:40960
	v_add_f32_e32 v239, v79, v239
	v_add_f32_e32 v197, v239, v197
	s_add_u32 m0, s5, 0x14800
	s_waitcnt lgkmcnt(4)
	v_mfma_f32_32x32x16_bf16 v[64:79], v[206:209], v[112:115], 0
	global_load_lds_dwordx4 v244, s[0:1]
	s_add_u32 m0, s5, 0x16800
	v_mfma_f32_32x32x16_bf16 v[64:79], v[210:213], v[116:119], v[64:79]
	global_load_lds_dwordx4 v245, s[0:1]
	v_mfma_f32_32x32x16_bf16 v[64:79], v[214:217], v[120:123], v[64:79]
	ds_read_b64_tr_b16 v[222:223], v188 offset:16384
	ds_read_b64_tr_b16 v[224:225], v188 offset:18432
	v_mfma_f32_32x32x16_bf16 v[64:79], v[218:221], v[124:127], v[64:79]
	ds_read_b64_tr_b16 v[226:227], v188 offset:16896
	ds_read_b64_tr_b16 v[228:229], v188 offset:18944
	v_exp_f32_e32 v96, v96
	v_exp_f32_e32 v97, v97
	s_waitcnt lgkmcnt(4)
	v_mfma_f32_32x32x16_bf16 v[64:79], v[160:163], v[128:131], v[64:79]
	ds_read_b64_tr_b16 v[230:231], v188 offset:17408
	ds_read_b64_tr_b16 v[232:233], v188 offset:19456
	v_exp_f32_e32 v98, v98
	v_exp_f32_e32 v99, v99
	v_exp_f32_e32 v100, v100
	v_mfma_f32_32x32x16_bf16 v[64:79], v[164:167], v[132:135], v[64:79]
	ds_read_b64_tr_b16 v[234:235], v188 offset:17920
	ds_read_b64_tr_b16 v[236:237], v188 offset:19968
	v_exp_f32_e32 v101, v101
	v_exp_f32_e32 v102, v102
	v_exp_f32_e32 v103, v103
	v_mfma_f32_32x32x16_bf16 v[64:79], v[168:171], v[136:139], v[64:79]
	ds_read_b64_tr_b16 v[240:241], v188 offset:20480
	ds_read_b64_tr_b16 v[242:243], v188 offset:22528
	v_exp_f32_e32 v104, v104
	v_exp_f32_e32 v105, v105
	v_mfma_f32_32x32x16_bf16 v[64:79], v[172:175], v[148:151], v[64:79]
	ds_read_b64_tr_b16 v[180:181], v188 offset:20992
	ds_read_b64_tr_b16 v[182:183], v188 offset:23040
	v_exp_f32_e32 v106, v106
	v_exp_f32_e32 v107, v107
	s_waitcnt lgkmcnt(6)
	v_mfma_f32_32x32x16_bf16 v[0:15], v[140:143], v[222:225], v[0:15]
	ds_read_b64_tr_b16 v[222:223], v188 offset:21504
	ds_read_b64_tr_b16 v[224:225], v188 offset:23552
	v_exp_f32_e32 v108, v108
	v_exp_f32_e32 v109, v109
	v_mfma_f32_32x32x16_bf16 v[16:31], v[140:143], v[226:229], v[16:31]
	ds_read_b64_tr_b16 v[226:227], v188 offset:22016
	ds_read_b64_tr_b16 v[228:229], v188 offset:24064
	v_exp_f32_e32 v110, v110
	v_exp_f32_e32 v111, v111
	v_mfma_f32_32x32x16_bf16 v[32:47], v[140:143], v[230:233], v[32:47]
	ds_read_b64_tr_b16 v[230:231], v188 offset:24576
	ds_read_b64_tr_b16 v[232:233], v188 offset:26624
	v_exp_f32_e32 v64, v64
	v_exp_f32_e32 v65, v65
	s_waitcnt lgkmcnt(6)
; __device__ __forceinline__ void qkt(f32x16& p0, f32x16& p1, const bf16* Ks, const bf16x8* qr, int r32, int hi) {
;   p0 = f32x16{}; p1 = f32x16{};
; #pragma unroll
;   for (int d0 = 0; d0 < 8; ++d0) { int cb = (d0 * 16 + hi * 8) * 2;
;     bf16x8 b0 = *reinterpret_cast<const bf16x8*>((const char*)Ks + KSWZ(r32, cb));
;     bf16x8 b1 = *reinterpret_cast<const bf16x8*>((const char*)Ks + KSWZ(32 + r32, cb));
;     p0 = __builtin_amdgcn_mfma_f32_32x32x16_bf16(b0, qr[d0], p0, 0, 0, 0);
;     p1 = __builtin_amdgcn_mfma_f32_32x32x16_bf16(b1, qr[d0], p1, 0, 0, 0); }
; }
; __device__ __forceinline__ int v_st(int k, int c) { const int kk = (k & ~0xC) | ((k & 4) << 1) | ((k & 8) >> 1); return ((kk >> 3) * 4 + (c >> 5)) * 512 + ((kk & 7) * 32 + (c & 31)) * 2; }
; __device__ __forceinline__ int v_rd_base(int lane) { return ((lane & 3) << 3) | (((lane >> 2) & 3) << 6) | (((lane >> 4) & 1) << 5) | (((lane >> 5) & 1) << 8); }
; template <int OFF> __device__ __forceinline__ s16x4 tr_read(int vb) {
;   s16x4 r; asm volatile("ds_read_b64_tr_b16 %0, %1 offset:%2" : "=&v"(r) : "v"(vb), "i"(OFF) : "memory"); return r;
; }
; template <int D0> __device__ __forceinline__ void pv_one(f32x16& od, int vb, bf16x8 pa0, bf16x8 pa1, bf16x8 pa2, bf16x8 pa3) {
;   const s16x4 l0 = tr_read<v_rd_off(D0, 0, 0)>(vb), h0 = tr_read<v_rd_off(D0, 0, 1)>(vb), l1 = tr_read<v_rd_off(D0, 1, 0)>(vb), h1 = tr_read<v_rd_off(D0, 1, 1)>(vb);
;   const s16x4 l2 = tr_read<v_rd_off(D0, 2, 0)>(vb), h2 = tr_read<v_rd_off(D0, 2, 1)>(vb), l3 = tr_read<v_rd_off(D0, 3, 0)>(vb), h3 = tr_read<v_rd_off(D0, 3, 1)>(vb);
;   asm volatile("s_waitcnt lgkmcnt(0)" ::: "memory"); SBAR();
;     ...
;   od = __builtin_amdgcn_mfma_f32_32x32x16_bf16(pa0, PK(l0, h0), od, 0, 0, 0);
;   od = __builtin_amdgcn_mfma_f32_32x32x16_bf16(pa1, PK(l1, h1), od, 0, 0, 0);
;   od = __builtin_amdgcn_mfma_f32_32x32x16_bf16(pa2, PK(l2, h2), od, 0, 0, 0);
;   od = __builtin_amdgcn_mfma_f32_32x32x16_bf16(pa3, PK(l3, h3), od, 0, 0, 0);
;     ...
; }
; __device__ __forceinline__ void partialSM_fast(f32x16& p0, f32x16& p1) {
; #pragma unroll
;   for (int r = 0; r < 16; ++r) p0[r] = __builtin_amdgcn_exp2f(p0[r]);
; }
; __device__ __forceinline__ void finishSM_fast(f32x16& p0, f32x16& p1, float& l_reg, bf16x8& pa0, bf16x8& pa1, bf16x8& pa2, bf16x8& pa3) {
; #pragma unroll
;   for (int r = 0; r < 16; ++r) p1[r] = __builtin_amdgcn_exp2f(p1[r]);
;   float ps = 0;
	v_mfma_f32_32x32x16_bf16 v[48:63], v[140:143], v[234:237], v[48:63]
	ds_read_b64_tr_b16 v[234:235], v188 offset:25088
	ds_read_b64_tr_b16 v[236:237], v188 offset:27136
	v_exp_f32_e32 v66, v66
	v_exp_f32_e32 v67, v67
	v_mfma_f32_32x32x16_bf16 v[0:15], v[144:147], v[240:243], v[0:15]
	ds_read_b64_tr_b16 v[240:241], v188 offset:25600
	ds_read_b64_tr_b16 v[242:243], v188 offset:27648
	v_exp_f32_e32 v68, v68
	v_exp_f32_e32 v69, v69
	v_cvt_pk_bf16_f32 v140, v96, v97
	v_cvt_pk_bf16_f32 v141, v98, v99
	v_mfma_f32_32x32x16_bf16 v[16:31], v[144:147], v[180:183], v[16:31]
	ds_read_b64_tr_b16 v[180:181], v188 offset:26112
	ds_read_b64_tr_b16 v[182:183], v188 offset:28160
	v_exp_f32_e32 v70, v70
	v_exp_f32_e32 v71, v71
	v_cvt_pk_bf16_f32 v142, v100, v101
	v_cvt_pk_bf16_f32 v143, v102, v103
	s_waitcnt lgkmcnt(6)
	v_mfma_f32_32x32x16_bf16 v[32:47], v[144:147], v[222:225], v[32:47]
	ds_read_b64_tr_b16 v[222:223], v188 offset:28672
	ds_read_b64_tr_b16 v[224:225], v188 offset:30720
	v_exp_f32_e32 v72, v72
	v_exp_f32_e32 v73, v73
	v_mfma_f32_32x32x16_bf16 v[48:63], v[144:147], v[226:229], v[48:63]
	ds_read_b64_tr_b16 v[226:227], v188 offset:29184
	ds_read_b64_tr_b16 v[228:229], v188 offset:31232
	v_exp_f32_e32 v74, v74
	v_exp_f32_e32 v75, v75
	v_mfma_f32_32x32x16_bf16 v[0:15], v[152:155], v[230:233], v[0:15]
	ds_read_b64_tr_b16 v[230:231], v188 offset:29696
	ds_read_b64_tr_b16 v[232:233], v188 offset:31744
	v_exp_f32_e32 v76, v76
	v_exp_f32_e32 v77, v77
	v_cvt_pk_bf16_f32 v144, v104, v105
	v_cvt_pk_bf16_f32 v145, v106, v107
	s_waitcnt lgkmcnt(6)
	v_mfma_f32_32x32x16_bf16 v[16:31], v[152:155], v[234:237], v[16:31]
	ds_read_b64_tr_b16 v[234:235], v188 offset:30208
	ds_read_b64_tr_b16 v[236:237], v188 offset:32256
	v_exp_f32_e32 v78, v78
	v_exp_f32_e32 v79, v79
	v_cvt_pk_bf16_f32 v146, v108, v109
	v_cvt_pk_bf16_f32 v147, v110, v111
	s_waitcnt vmcnt(6)
	s_barrier
	v_mfma_f32_32x32x16_bf16 v[32:47], v[152:155], v[240:243], v[32:47]
	s_add_u32 m0, s5, 0x0
	v_add_f32_e32 v238, v96, v97
	global_load_lds_dwordx4 v253, s[0:1]
	v_add_f32_e32 v238, v98, v238
	v_add_f32_e32 v238, v99, v238
	v_mfma_f32_32x32x16_bf16 v[48:63], v[152:155], v[180:183], v[48:63]
	s_add_u32 m0, s5, 0x2000
	v_add_f32_e32 v238, v100, v238
	global_load_lds_dwordx4 v254, s[0:1]
	v_add_f32_e32 v238, v101, v238
	v_add_f32_e32 v238, v102, v238
	s_add_u32 s0, s0, 0x4000
	s_addc_u32 s1, s1, 0
	s_waitcnt lgkmcnt(2)
	v_mfma_f32_32x32x16_bf16 v[0:15], v[156:159], v[222:225], v[0:15]
	v_add_f32_e32 v238, v103, v238
	v_add_f32_e32 v238, v104, v238
	v_add_f32_e32 v238, v105, v238
	ds_read_b128 v[206:209], v194 offset:49152
	ds_read_b128 v[210:213], v196 offset:49152
	v_mfma_f32_32x32x16_bf16 v[16:31], v[156:159], v[226:229], v[16:31]
	v_add_f32_e32 v238, v106, v238
	v_add_f32_e32 v238, v107, v238
	v_add_f32_e32 v238, v108, v238
	ds_read_b128 v[214:217], v198 offset:49152
	ds_read_b128 v[218:221], v199 offset:49152
	v_mfma_f32_32x32x16_bf16 v[32:47], v[156:159], v[230:233], v[32:47]
	v_add_f32_e32 v238, v109, v238
	v_add_f32_e32 v238, v110, v238
	ds_read_b128 v[160:163], v200 offset:49152
	ds_read_b128 v[164:167], v201 offset:49152
	s_waitcnt lgkmcnt(6)
	v_mfma_f32_32x32x16_bf16 v[48:63], v[156:159], v[234:237], v[48:63]
	v_add_f32_e32 v238, v111, v238
	v_add_f32_e32 v197, v238, v197
	ds_read_b128 v[168:171], v202 offset:49152
	ds_read_b128 v[172:175], v203 offset:49152
	s_waitcnt lgkmcnt(4)
	v_mfma_f32_32x32x16_bf16 v[96:111], v[206:209], v[112:115], 0
	ds_read_b128 v[206:209], v194 offset:57344
	v_cvt_pk_bf16_f32 v152, v64, v65
	v_cvt_pk_bf16_f32 v153, v66, v67
	v_add_f32_e32 v239, v64, v65
	v_add_f32_e32 v239, v66, v239
	v_mfma_f32_32x32x16_bf16 v[96:111], v[210:213], v[116:119], v[96:111]
	ds_read_b128 v[210:213], v196 offset:57344
	v_cvt_pk_bf16_f32 v154, v68, v69
	v_cvt_pk_bf16_f32 v155, v70, v71
	v_add_f32_e32 v239, v67, v239
	v_add_f32_e32 v239, v68, v239
	v_mfma_f32_32x32x16_bf16 v[96:111], v[214:217], v[120:123], v[96:111]
	ds_read_b128 v[214:217], v198 offset:57344
	v_add_f32_e32 v239, v69, v239
	v_add_f32_e32 v239, v70, v239
	v_mfma_f32_32x32x16_bf16 v[96:111], v[218:221], v[124:127], v[96:111]
	ds_read_b128 v[218:221], v199 offset:57344
	v_add_f32_e32 v239, v71, v239
	v_add_f32_e32 v239, v72, v239
	s_waitcnt lgkmcnt(4)
	v_mfma_f32_32x32x16_bf16 v[96:111], v[160:163], v[128:131], v[96:111]
	ds_read_b128 v[160:163], v200 offset:57344
	v_cvt_pk_bf16_f32 v156, v72, v73
	v_cvt_pk_bf16_f32 v157, v74, v75
	v_add_f32_e32 v239, v73, v239
	v_add_f32_e32 v239, v74, v239
	v_mfma_f32_32x32x16_bf16 v[96:111], v[164:167], v[132:135], v[96:111]
	ds_read_b128 v[164:167], v201 offset:57344
	v_cvt_pk_bf16_f32 v158, v76, v77
	v_cvt_pk_bf16_f32 v159, v78, v79
	v_add_f32_e32 v239, v75, v239
	v_add_f32_e32 v239, v76, v239
	v_mfma_f32_32x32x16_bf16 v[96:111], v[168:171], v[136:139], v[96:111]
	ds_read_b128 v[168:171], v202 offset:57344
	v_add_f32_e32 v239, v77, v239
	v_add_f32_e32 v239, v78, v239
	v_mfma_f32_32x32x16_bf16 v[96:111], v[172:175], v[148:151], v[96:111]
	ds_read_b128 v[172:175], v203 offset:57344
	v_add_f32_e32 v239, v79, v239
	v_add_f32_e32 v197, v239, v197
	s_add_u32 m0, s5, 0x18800
	s_waitcnt lgkmcnt(4)
	v_mfma_f32_32x32x16_bf16 v[64:79], v[206:209], v[112:115], 0
	global_load_lds_dwordx4 v244, s[0:1]
	s_add_u32 m0, s5, 0x1a800
	v_mfma_f32_32x32x16_bf16 v[64:79], v[210:213], v[116:119], v[64:79]
	global_load_lds_dwordx4 v245, s[0:1]
	v_mfma_f32_32x32x16_bf16 v[64:79], v[214:217], v[120:123], v[64:79]
	ds_read_b64_tr_b16 v[222:223], v188 offset:32768
	ds_read_b64_tr_b16 v[224:225], v188 offset:34816
	v_mfma_f32_32x32x16_bf16 v[64:79], v[218:221], v[124:127], v[64:79]
	ds_read_b64_tr_b16 v[226:227], v188 offset:33280
	ds_read_b64_tr_b16 v[228:229], v188 offset:35328
	v_exp_f32_e32 v96, v96
	v_exp_f32_e32 v97, v97
	s_waitcnt lgkmcnt(4)
; __device__ __forceinline__ void qkt(f32x16& p0, f32x16& p1, const bf16* Ks, const bf16x8* qr, int r32, int hi) {
;   p0 = f32x16{}; p1 = f32x16{};
; #pragma unroll
;   for (int d0 = 0; d0 < 8; ++d0) { int cb = (d0 * 16 + hi * 8) * 2;
;     bf16x8 b0 = *reinterpret_cast<const bf16x8*>((const char*)Ks + KSWZ(r32, cb));
;     bf16x8 b1 = *reinterpret_cast<const bf16x8*>((const char*)Ks + KSWZ(32 + r32, cb));
;     p0 = __builtin_amdgcn_mfma_f32_32x32x16_bf16(b0, qr[d0], p0, 0, 0, 0);
;     p1 = __builtin_amdgcn_mfma_f32_32x32x16_bf16(b1, qr[d0], p1, 0, 0, 0); }
; }
; __device__ __forceinline__ int v_st(int k, int c) { const int kk = (k & ~0xC) | ((k & 4) << 1) | ((k & 8) >> 1); return ((kk >> 3) * 4 + (c >> 5)) * 512 + ((kk & 7) * 32 + (c & 31)) * 2; }
; __device__ __forceinline__ int v_rd_base(int lane) { return ((lane & 3) << 3) | (((lane >> 2) & 3) << 6) | (((lane >> 4) & 1) << 5) | (((lane >> 5) & 1) << 8); }
; template <int OFF> __device__ __forceinline__ s16x4 tr_read(int vb) {
;   s16x4 r; asm volatile("ds_read_b64_tr_b16 %0, %1 offset:%2" : "=&v"(r) : "v"(vb), "i"(OFF) : "memory"); return r;
; }
; template <int D0> __device__ __forceinline__ void pv_one(f32x16& od, int vb, bf16x8 pa0, bf16x8 pa1, bf16x8 pa2, bf16x8 pa3) {
;   const s16x4 l0 = tr_read<v_rd_off(D0, 0, 0)>(vb), h0 = tr_read<v_rd_off(D0, 0, 1)>(vb), l1 = tr_read<v_rd_off(D0, 1, 0)>(vb), h1 = tr_read<v_rd_off(D0, 1, 1)>(vb);
;   const s16x4 l2 = tr_read<v_rd_off(D0, 2, 0)>(vb), h2 = tr_read<v_rd_off(D0, 2, 1)>(vb), l3 = tr_read<v_rd_off(D0, 3, 0)>(vb), h3 = tr_read<v_rd_off(D0, 3, 1)>(vb);
;   asm volatile("s_waitcnt lgkmcnt(0)" ::: "memory"); SBAR();
;     ...
;   od = __builtin_amdgcn_mfma_f32_32x32x16_bf16(pa0, PK(l0, h0), od, 0, 0, 0);
;   od = __builtin_amdgcn_mfma_f32_32x32x16_bf16(pa1, PK(l1, h1), od, 0, 0, 0);
;   od = __builtin_amdgcn_mfma_f32_32x32x16_bf16(pa2, PK(l2, h2), od, 0, 0, 0);
;   od = __builtin_amdgcn_mfma_f32_32x32x16_bf16(pa3, PK(l3, h3), od, 0, 0, 0);
;     ...
; }
; __device__ __forceinline__ void partialSM_fast(f32x16& p0, f32x16& p1) {
; #pragma unroll
;   for (int r = 0; r < 16; ++r) p0[r] = __builtin_amdgcn_exp2f(p0[r]);
; }
; __device__ __forceinline__ void finishSM_fast(f32x16& p0, f32x16& p1, float& l_reg, bf16x8& pa0, bf16x8& pa1, bf16x8& pa2, bf16x8& pa3) {
; #pragma unroll
;   for (int r = 0; r < 16; ++r) p1[r] = __builtin_amdgcn_exp2f(p1[r]);
;   float ps = 0;
	v_mfma_f32_32x32x16_bf16 v[64:79], v[160:163], v[128:131], v[64:79]
	ds_read_b64_tr_b16 v[230:231], v188 offset:33792
	ds_read_b64_tr_b16 v[232:233], v188 offset:35840
	v_exp_f32_e32 v98, v98
	v_exp_f32_e32 v99, v99
	v_exp_f32_e32 v100, v100
	v_mfma_f32_32x32x16_bf16 v[64:79], v[164:167], v[132:135], v[64:79]
	ds_read_b64_tr_b16 v[234:235], v188 offset:34304
	ds_read_b64_tr_b16 v[236:237], v188 offset:36352
	v_exp_f32_e32 v101, v101
	v_exp_f32_e32 v102, v102
	v_exp_f32_e32 v103, v103
	v_mfma_f32_32x32x16_bf16 v[64:79], v[168:171], v[136:139], v[64:79]
	ds_read_b64_tr_b16 v[240:241], v188 offset:36864
	ds_read_b64_tr_b16 v[242:243], v188 offset:38912
	v_exp_f32_e32 v104, v104
	v_exp_f32_e32 v105, v105
	v_mfma_f32_32x32x16_bf16 v[64:79], v[172:175], v[148:151], v[64:79]
	ds_read_b64_tr_b16 v[180:181], v188 offset:37376
	ds_read_b64_tr_b16 v[182:183], v188 offset:39424
	v_exp_f32_e32 v106, v106
	v_exp_f32_e32 v107, v107
	s_waitcnt lgkmcnt(6)
	v_mfma_f32_32x32x16_bf16 v[0:15], v[140:143], v[222:225], v[0:15]
	ds_read_b64_tr_b16 v[222:223], v188 offset:37888
	ds_read_b64_tr_b16 v[224:225], v188 offset:39936
	v_exp_f32_e32 v108, v108
	v_exp_f32_e32 v109, v109
	v_mfma_f32_32x32x16_bf16 v[16:31], v[140:143], v[226:229], v[16:31]
	ds_read_b64_tr_b16 v[226:227], v188 offset:38400
	ds_read_b64_tr_b16 v[228:229], v188 offset:40448
	v_exp_f32_e32 v110, v110
	v_exp_f32_e32 v111, v111
	v_mfma_f32_32x32x16_bf16 v[32:47], v[140:143], v[230:233], v[32:47]
	ds_read_b64_tr_b16 v[230:231], v188 offset:40960
	ds_read_b64_tr_b16 v[232:233], v188 offset:43008
	v_exp_f32_e32 v64, v64
	v_exp_f32_e32 v65, v65
	s_waitcnt lgkmcnt(6)
	v_mfma_f32_32x32x16_bf16 v[48:63], v[140:143], v[234:237], v[48:63]
	ds_read_b64_tr_b16 v[234:235], v188 offset:41472
	ds_read_b64_tr_b16 v[236:237], v188 offset:43520
	v_exp_f32_e32 v66, v66
	v_exp_f32_e32 v67, v67
	v_mfma_f32_32x32x16_bf16 v[0:15], v[144:147], v[240:243], v[0:15]
	ds_read_b64_tr_b16 v[240:241], v188 offset:41984
	ds_read_b64_tr_b16 v[242:243], v188 offset:44032
	v_exp_f32_e32 v68, v68
	v_exp_f32_e32 v69, v69
	v_cvt_pk_bf16_f32 v140, v96, v97
	v_cvt_pk_bf16_f32 v141, v98, v99
	v_mfma_f32_32x32x16_bf16 v[16:31], v[144:147], v[180:183], v[16:31]
	ds_read_b64_tr_b16 v[180:181], v188 offset:42496
	ds_read_b64_tr_b16 v[182:183], v188 offset:44544
	v_exp_f32_e32 v70, v70
	v_exp_f32_e32 v71, v71
	v_cvt_pk_bf16_f32 v142, v100, v101
	v_cvt_pk_bf16_f32 v143, v102, v103
	s_waitcnt lgkmcnt(6)
	v_mfma_f32_32x32x16_bf16 v[32:47], v[144:147], v[222:225], v[32:47]
	ds_read_b64_tr_b16 v[222:223], v188 offset:45056
	ds_read_b64_tr_b16 v[224:225], v188 offset:47104
	v_exp_f32_e32 v72, v72
	v_exp_f32_e32 v73, v73
	v_mfma_f32_32x32x16_bf16 v[48:63], v[144:147], v[226:229], v[48:63]
	ds_read_b64_tr_b16 v[226:227], v188 offset:45568
	ds_read_b64_tr_b16 v[228:229], v188 offset:47616
	v_exp_f32_e32 v74, v74
	v_exp_f32_e32 v75, v75
	v_mfma_f32_32x32x16_bf16 v[0:15], v[152:155], v[230:233], v[0:15]
	ds_read_b64_tr_b16 v[230:231], v188 offset:46080
	ds_read_b64_tr_b16 v[232:233], v188 offset:48128
	v_exp_f32_e32 v76, v76
	v_exp_f32_e32 v77, v77
	v_cvt_pk_bf16_f32 v144, v104, v105
	v_cvt_pk_bf16_f32 v145, v106, v107
	s_waitcnt lgkmcnt(6)
	v_mfma_f32_32x32x16_bf16 v[16:31], v[152:155], v[234:237], v[16:31]
	ds_read_b64_tr_b16 v[234:235], v188 offset:46592
	ds_read_b64_tr_b16 v[236:237], v188 offset:48640
	v_exp_f32_e32 v78, v78
	v_exp_f32_e32 v79, v79
	v_cvt_pk_bf16_f32 v146, v108, v109
	v_cvt_pk_bf16_f32 v147, v110, v111
	s_waitcnt vmcnt(6)
	s_barrier
	v_mfma_f32_32x32x16_bf16 v[32:47], v[152:155], v[240:243], v[32:47]
	s_add_u32 m0, s5, 0x4000
	v_add_f32_e32 v238, v96, v97
	global_load_lds_dwordx4 v253, s[0:1]
	v_add_f32_e32 v238, v98, v238
	v_add_f32_e32 v238, v99, v238
	v_mfma_f32_32x32x16_bf16 v[48:63], v[152:155], v[180:183], v[48:63]
	s_add_u32 m0, s5, 0x6000
	v_add_f32_e32 v238, v100, v238
	global_load_lds_dwordx4 v254, s[0:1]
	v_add_f32_e32 v238, v101, v238
	v_add_f32_e32 v238, v102, v238
	s_add_u32 s0, s0, 0x4000
	s_addc_u32 s1, s1, 0
	s_waitcnt lgkmcnt(2)
	v_mfma_f32_32x32x16_bf16 v[0:15], v[156:159], v[222:225], v[0:15]
	v_add_f32_e32 v238, v103, v238
	v_add_f32_e32 v238, v104, v238
	v_add_f32_e32 v238, v105, v238
	ds_read_b128 v[206:209], v194
	ds_read_b128 v[210:213], v196
	v_mfma_f32_32x32x16_bf16 v[16:31], v[156:159], v[226:229], v[16:31]
	v_add_f32_e32 v238, v106, v238
	v_add_f32_e32 v238, v107, v238
	v_add_f32_e32 v238, v108, v238
	ds_read_b128 v[214:217], v198
	ds_read_b128 v[218:221], v199
	v_mfma_f32_32x32x16_bf16 v[32:47], v[156:159], v[230:233], v[32:47]
	v_add_f32_e32 v238, v109, v238
	v_add_f32_e32 v238, v110, v238
	ds_read_b128 v[160:163], v200
	ds_read_b128 v[164:167], v201
	s_waitcnt lgkmcnt(6)
	v_mfma_f32_32x32x16_bf16 v[48:63], v[156:159], v[234:237], v[48:63]
	v_add_f32_e32 v238, v111, v238
	v_add_f32_e32 v197, v238, v197
	ds_read_b128 v[168:171], v202
	ds_read_b128 v[172:175], v203
	s_waitcnt lgkmcnt(4)
	v_mfma_f32_32x32x16_bf16 v[96:111], v[206:209], v[112:115], 0
	ds_read_b128 v[206:209], v194 offset:8192
	v_cvt_pk_bf16_f32 v152, v64, v65
	v_cvt_pk_bf16_f32 v153, v66, v67
	v_add_f32_e32 v239, v64, v65
	v_add_f32_e32 v239, v66, v239
	v_mfma_f32_32x32x16_bf16 v[96:111], v[210:213], v[116:119], v[96:111]
	ds_read_b128 v[210:213], v196 offset:8192
	v_cvt_pk_bf16_f32 v154, v68, v69
	v_cvt_pk_bf16_f32 v155, v70, v71
	v_add_f32_e32 v239, v67, v239
	v_add_f32_e32 v239, v68, v239
	v_mfma_f32_32x32x16_bf16 v[96:111], v[214:217], v[120:123], v[96:111]
	ds_read_b128 v[214:217], v198 offset:8192
	v_add_f32_e32 v239, v69, v239
	v_add_f32_e32 v239, v70, v239
	v_mfma_f32_32x32x16_bf16 v[96:111], v[218:221], v[124:127], v[96:111]
	ds_read_b128 v[218:221], v199 offset:8192
	v_add_f32_e32 v239, v71, v239
	v_add_f32_e32 v239, v72, v239
	s_waitcnt lgkmcnt(4)
; __device__ __forceinline__ void qkt(f32x16& p0, f32x16& p1, const bf16* Ks, const bf16x8* qr, int r32, int hi) {
;   p0 = f32x16{}; p1 = f32x16{};
; #pragma unroll
;   for (int d0 = 0; d0 < 8; ++d0) { int cb = (d0 * 16 + hi * 8) * 2;
;     bf16x8 b0 = *reinterpret_cast<const bf16x8*>((const char*)Ks + KSWZ(r32, cb));
;     bf16x8 b1 = *reinterpret_cast<const bf16x8*>((const char*)Ks + KSWZ(32 + r32, cb));
;     p0 = __builtin_amdgcn_mfma_f32_32x32x16_bf16(b0, qr[d0], p0, 0, 0, 0);
;     p1 = __builtin_amdgcn_mfma_f32_32x32x16_bf16(b1, qr[d0], p1, 0, 0, 0); }
; }
; __device__ __forceinline__ int v_st(int k, int c) { const int kk = (k & ~0xC) | ((k & 4) << 1) | ((k & 8) >> 1); return ((kk >> 3) * 4 + (c >> 5)) * 512 + ((kk & 7) * 32 + (c & 31)) * 2; }
; __device__ __forceinline__ int v_rd_base(int lane) { return ((lane & 3) << 3) | (((lane >> 2) & 3) << 6) | (((lane >> 4) & 1) << 5) | (((lane >> 5) & 1) << 8); }
; template <int OFF> __device__ __forceinline__ s16x4 tr_read(int vb) {
;   s16x4 r; asm volatile("ds_read_b64_tr_b16 %0, %1 offset:%2" : "=&v"(r) : "v"(vb), "i"(OFF) : "memory"); return r;
; }
; template <int D0> __device__ __forceinline__ void pv_one(f32x16& od, int vb, bf16x8 pa0, bf16x8 pa1, bf16x8 pa2, bf16x8 pa3) {
;   const s16x4 l0 = tr_read<v_rd_off(D0, 0, 0)>(vb), h0 = tr_read<v_rd_off(D0, 0, 1)>(vb), l1 = tr_read<v_rd_off(D0, 1, 0)>(vb), h1 = tr_read<v_rd_off(D0, 1, 1)>(vb);
;   const s16x4 l2 = tr_read<v_rd_off(D0, 2, 0)>(vb), h2 = tr_read<v_rd_off(D0, 2, 1)>(vb), l3 = tr_read<v_rd_off(D0, 3, 0)>(vb), h3 = tr_read<v_rd_off(D0, 3, 1)>(vb);
;   asm volatile("s_waitcnt lgkmcnt(0)" ::: "memory"); SBAR();
;     ...
;   od = __builtin_amdgcn_mfma_f32_32x32x16_bf16(pa0, PK(l0, h0), od, 0, 0, 0);
;   od = __builtin_amdgcn_mfma_f32_32x32x16_bf16(pa1, PK(l1, h1), od, 0, 0, 0);
;   od = __builtin_amdgcn_mfma_f32_32x32x16_bf16(pa2, PK(l2, h2), od, 0, 0, 0);
;   od = __builtin_amdgcn_mfma_f32_32x32x16_bf16(pa3, PK(l3, h3), od, 0, 0, 0);
;     ...
; }
; __device__ __forceinline__ void partialSM_fast(f32x16& p0, f32x16& p1) {
; #pragma unroll
;   for (int r = 0; r < 16; ++r) p0[r] = __builtin_amdgcn_exp2f(p0[r]);
; }
; __device__ __forceinline__ void finishSM_fast(f32x16& p0, f32x16& p1, float& l_reg, bf16x8& pa0, bf16x8& pa1, bf16x8& pa2, bf16x8& pa3) {
; #pragma unroll
;   for (int r = 0; r < 16; ++r) p1[r] = __builtin_amdgcn_exp2f(p1[r]);
;   float ps = 0;
	v_mfma_f32_32x32x16_bf16 v[96:111], v[160:163], v[128:131], v[96:111]
	ds_read_b128 v[160:163], v200 offset:8192
	v_cvt_pk_bf16_f32 v156, v72, v73
	v_cvt_pk_bf16_f32 v157, v74, v75
	v_add_f32_e32 v239, v73, v239
	v_add_f32_e32 v239, v74, v239
	v_mfma_f32_32x32x16_bf16 v[96:111], v[164:167], v[132:135], v[96:111]
	ds_read_b128 v[164:167], v201 offset:8192
	v_cvt_pk_bf16_f32 v158, v76, v77
	v_cvt_pk_bf16_f32 v159, v78, v79
	v_add_f32_e32 v239, v75, v239
	v_add_f32_e32 v239, v76, v239
	v_mfma_f32_32x32x16_bf16 v[96:111], v[168:171], v[136:139], v[96:111]
	ds_read_b128 v[168:171], v202 offset:8192
	v_add_f32_e32 v239, v77, v239
	v_add_f32_e32 v239, v78, v239
	v_mfma_f32_32x32x16_bf16 v[96:111], v[172:175], v[148:151], v[96:111]
	ds_read_b128 v[172:175], v203 offset:8192
	v_add_f32_e32 v239, v79, v239
	v_add_f32_e32 v197, v239, v197
	s_add_u32 m0, s5, 0x1c800
	s_waitcnt lgkmcnt(4)
	v_mfma_f32_32x32x16_bf16 v[64:79], v[206:209], v[112:115], 0
	global_load_lds_dwordx4 v244, s[0:1]
	s_add_u32 m0, s5, 0x1e800
	v_mfma_f32_32x32x16_bf16 v[64:79], v[210:213], v[116:119], v[64:79]
	global_load_lds_dwordx4 v245, s[0:1]
	v_mfma_f32_32x32x16_bf16 v[64:79], v[214:217], v[120:123], v[64:79]
	ds_read_b64_tr_b16 v[222:223], v188 offset:49152
	ds_read_b64_tr_b16 v[224:225], v188 offset:51200
	v_mfma_f32_32x32x16_bf16 v[64:79], v[218:221], v[124:127], v[64:79]
	ds_read_b64_tr_b16 v[226:227], v188 offset:49664
	ds_read_b64_tr_b16 v[228:229], v188 offset:51712
	v_exp_f32_e32 v96, v96
	v_exp_f32_e32 v97, v97
	s_waitcnt lgkmcnt(4)
	v_mfma_f32_32x32x16_bf16 v[64:79], v[160:163], v[128:131], v[64:79]
	ds_read_b64_tr_b16 v[230:231], v188 offset:50176
	ds_read_b64_tr_b16 v[232:233], v188 offset:52224
	v_exp_f32_e32 v98, v98
	v_exp_f32_e32 v99, v99
	v_exp_f32_e32 v100, v100
	v_mfma_f32_32x32x16_bf16 v[64:79], v[164:167], v[132:135], v[64:79]
	ds_read_b64_tr_b16 v[234:235], v188 offset:50688
	ds_read_b64_tr_b16 v[236:237], v188 offset:52736
	v_exp_f32_e32 v101, v101
	v_exp_f32_e32 v102, v102
	v_exp_f32_e32 v103, v103
	v_mfma_f32_32x32x16_bf16 v[64:79], v[168:171], v[136:139], v[64:79]
	ds_read_b64_tr_b16 v[240:241], v188 offset:53248
	ds_read_b64_tr_b16 v[242:243], v188 offset:55296
	v_exp_f32_e32 v104, v104
	v_exp_f32_e32 v105, v105
	v_mfma_f32_32x32x16_bf16 v[64:79], v[172:175], v[148:151], v[64:79]
	ds_read_b64_tr_b16 v[180:181], v188 offset:53760
	ds_read_b64_tr_b16 v[182:183], v188 offset:55808
	v_exp_f32_e32 v106, v106
	v_exp_f32_e32 v107, v107
	s_waitcnt lgkmcnt(6)
	v_mfma_f32_32x32x16_bf16 v[0:15], v[140:143], v[222:225], v[0:15]
	ds_read_b64_tr_b16 v[222:223], v188 offset:54272
	ds_read_b64_tr_b16 v[224:225], v188 offset:56320
	v_exp_f32_e32 v108, v108
	v_exp_f32_e32 v109, v109
	v_mfma_f32_32x32x16_bf16 v[16:31], v[140:143], v[226:229], v[16:31]
	ds_read_b64_tr_b16 v[226:227], v188 offset:54784
	ds_read_b64_tr_b16 v[228:229], v188 offset:56832
	v_exp_f32_e32 v110, v110
	v_exp_f32_e32 v111, v111
	v_mfma_f32_32x32x16_bf16 v[32:47], v[140:143], v[230:233], v[32:47]
	ds_read_b64_tr_b16 v[230:231], v188 offset:57344
	ds_read_b64_tr_b16 v[232:233], v188 offset:59392
	v_exp_f32_e32 v64, v64
	v_exp_f32_e32 v65, v65
	s_waitcnt lgkmcnt(6)
	v_mfma_f32_32x32x16_bf16 v[48:63], v[140:143], v[234:237], v[48:63]
	ds_read_b64_tr_b16 v[234:235], v188 offset:57856
	ds_read_b64_tr_b16 v[236:237], v188 offset:59904
	v_exp_f32_e32 v66, v66
	v_exp_f32_e32 v67, v67
	v_mfma_f32_32x32x16_bf16 v[0:15], v[144:147], v[240:243], v[0:15]
	ds_read_b64_tr_b16 v[240:241], v188 offset:58368
	ds_read_b64_tr_b16 v[242:243], v188 offset:60416
	v_exp_f32_e32 v68, v68
	v_exp_f32_e32 v69, v69
	v_cvt_pk_bf16_f32 v140, v96, v97
	v_cvt_pk_bf16_f32 v141, v98, v99
	v_mfma_f32_32x32x16_bf16 v[16:31], v[144:147], v[180:183], v[16:31]
	ds_read_b64_tr_b16 v[180:181], v188 offset:58880
	ds_read_b64_tr_b16 v[182:183], v188 offset:60928
	v_exp_f32_e32 v70, v70
	v_exp_f32_e32 v71, v71
	v_cvt_pk_bf16_f32 v142, v100, v101
	v_cvt_pk_bf16_f32 v143, v102, v103
	s_waitcnt lgkmcnt(6)
	v_mfma_f32_32x32x16_bf16 v[32:47], v[144:147], v[222:225], v[32:47]
	ds_read_b64_tr_b16 v[222:223], v188 offset:61440
	ds_read_b64_tr_b16 v[224:225], v188 offset:63488
	v_exp_f32_e32 v72, v72
	v_exp_f32_e32 v73, v73
	v_mfma_f32_32x32x16_bf16 v[48:63], v[144:147], v[226:229], v[48:63]
	ds_read_b64_tr_b16 v[226:227], v188 offset:61952
	ds_read_b64_tr_b16 v[228:229], v188 offset:64000
	v_exp_f32_e32 v74, v74
	v_exp_f32_e32 v75, v75
	v_mfma_f32_32x32x16_bf16 v[0:15], v[152:155], v[230:233], v[0:15]
	ds_read_b64_tr_b16 v[230:231], v188 offset:62464
	ds_read_b64_tr_b16 v[232:233], v188 offset:64512
	v_exp_f32_e32 v76, v76
	v_exp_f32_e32 v77, v77
	v_cvt_pk_bf16_f32 v144, v104, v105
	v_cvt_pk_bf16_f32 v145, v106, v107
	s_waitcnt lgkmcnt(6)
	v_mfma_f32_32x32x16_bf16 v[16:31], v[152:155], v[234:237], v[16:31]
	ds_read_b64_tr_b16 v[234:235], v188 offset:62976
	ds_read_b64_tr_b16 v[236:237], v188 offset:65024
	v_exp_f32_e32 v78, v78
	v_exp_f32_e32 v79, v79
	v_cvt_pk_bf16_f32 v146, v108, v109
	v_cvt_pk_bf16_f32 v147, v110, v111
	s_waitcnt vmcnt(6)
	s_barrier
; #define SBAR() __builtin_amdgcn_sched_barrier(0)
; #define SWAIT() asm volatile("s_waitcnt vmcnt(4)" ::: "memory")
; #define MASKLAST(P0, P1) do { _Pragma("unroll") for (int r = 8; r < 16; ++r) P0[r] = -1e30f; _Pragma("unroll") for (int r = 0; r < 16; ++r) P1[r] = -1e30f; } while (0)
; template <int D0> __device__ __forceinline__ void pv_one(f32x16& od, int vb, bf16x8 pa0, bf16x8 pa1, bf16x8 pa2, bf16x8 pa3) {
;   const s16x4 l0 = tr_read<v_rd_off(D0, 0, 0)>(vb), h0 = tr_read<v_rd_off(D0, 0, 1)>(vb), l1 = tr_read<v_rd_off(D0, 1, 0)>(vb), h1 = tr_read<v_rd_off(D0, 1, 1)>(vb);
;   const s16x4 l2 = tr_read<v_rd_off(D0, 2, 0)>(vb), h2 = tr_read<v_rd_off(D0, 2, 1)>(vb), l3 = tr_read<v_rd_off(D0, 3, 0)>(vb), h3 = tr_read<v_rd_off(D0, 3, 1)>(vb);
;   asm volatile("s_waitcnt lgkmcnt(0)" ::: "memory"); SBAR();
;     ...
;   od = __builtin_amdgcn_mfma_f32_32x32x16_bf16(pa0, PK(l0, h0), od, 0, 0, 0);
;   od = __builtin_amdgcn_mfma_f32_32x32x16_bf16(pa1, PK(l1, h1), od, 0, 0, 0);
;   od = __builtin_amdgcn_mfma_f32_32x32x16_bf16(pa2, PK(l2, h2), od, 0, 0, 0);
;   od = __builtin_amdgcn_mfma_f32_32x32x16_bf16(pa3, PK(l3, h3), od, 0, 0, 0);
;     ...
; }
; __device__ __forceinline__ void attn_unit_fast(const bf16* __restrict__ Qb, const bf16* __restrict__ Kh, const bf16* __restrict__ Vh, bf16* __restrict__ Ob, int NT, char* lds, int t0, const float* __restrict__ qg) {
;     ...
;   for (int j = 1; j + 1 < NT; j += 2) {
;     SBAR(); qkt(pB0, pB1, (bf16*)((char*)K_lds + SHM_K), qr, r32, hi);
;     finishSM_fast(pA0, pA1, l_reg, pa0, pa1, pa2, pa3); SBAR();
;     if (j + 2 < NT) SLOAD(SO, (j + 2) * KVBLK); SBAR();
;     pv_d0(o, vb0, pa0, pa1, pa2, pa3); partialSM_fast(pB0, pB1);
;     __syncthreads(); SWAIT(); SWRITE(0, SE);
;     __syncthreads();
;     SBAR(); qkt(pA0, pA1, K_lds, qr, r32, hi);
;     if (j + 2 == NT) MASKLAST(pA0, pA1);
;     finishSM_fast(pB0, pB1, l_reg, pa0, pa1, pa2, pa3); SBAR();
;     if (j + 3 < NT) SLOAD(SE, (j + 3) * KVBLK); SBAR();
;     pv_d0(o, vb0 + (int)SHM_V, pa0, pa1, pa2, pa3); partialSM_fast(pA0, pA1);
;     __syncthreads(); SWAIT(); SWRITE(1, SO);
;     __syncthreads();
;   }
;   finishSM_fast(pA0, pA1, l_reg, pa0, pa1, pa2, pa3); SBAR();
;   pv_d0(o, vb0, pa0, pa1, pa2, pa3);
;   { int r32e = r32; asm volatile("" : "+v"(r32e)); if (hi == 0) li_l[r32e] = l_reg; }
;   asm volatile("s_waitcnt lgkmcnt(0)" ::: "memory");
	v_mfma_f32_32x32x16_bf16 v[32:47], v[152:155], v[240:243], v[32:47]
	s_add_u32 m0, s5, 0x8000
	v_add_f32_e32 v238, v96, v97
	global_load_lds_dwordx4 v253, s[0:1]
	v_add_f32_e32 v238, v98, v238
	v_add_f32_e32 v238, v99, v238
	v_mfma_f32_32x32x16_bf16 v[48:63], v[152:155], v[180:183], v[48:63]
	s_add_u32 m0, s5, 0xa000
	v_add_f32_e32 v238, v100, v238
	global_load_lds_dwordx4 v254, s[0:1]
	v_add_f32_e32 v238, v101, v238
	v_add_f32_e32 v238, v102, v238
	s_add_u32 s0, s0, 0x4000
	s_addc_u32 s1, s1, 0
	s_waitcnt lgkmcnt(2)
	v_mfma_f32_32x32x16_bf16 v[0:15], v[156:159], v[222:225], v[0:15]
	v_add_f32_e32 v238, v103, v238
	v_add_f32_e32 v238, v104, v238
	v_add_f32_e32 v238, v105, v238
	ds_read_b128 v[206:209], v194 offset:16384
	ds_read_b128 v[210:213], v196 offset:16384
	v_mfma_f32_32x32x16_bf16 v[16:31], v[156:159], v[226:229], v[16:31]
	v_add_f32_e32 v238, v106, v238
	v_add_f32_e32 v238, v107, v238
	v_add_f32_e32 v238, v108, v238
	ds_read_b128 v[214:217], v198 offset:16384
	ds_read_b128 v[218:221], v199 offset:16384
	v_mfma_f32_32x32x16_bf16 v[32:47], v[156:159], v[230:233], v[32:47]
	v_add_f32_e32 v238, v109, v238
	v_add_f32_e32 v238, v110, v238
	ds_read_b128 v[160:163], v200 offset:16384
	ds_read_b128 v[164:167], v201 offset:16384
	s_waitcnt lgkmcnt(6)
	v_mfma_f32_32x32x16_bf16 v[48:63], v[156:159], v[234:237], v[48:63]
	v_add_f32_e32 v238, v111, v238
	v_add_f32_e32 v197, v238, v197
	ds_read_b128 v[168:171], v202 offset:16384
	ds_read_b128 v[172:175], v203 offset:16384
	s_sub_u32 s4, s4, 1
	s_cmp_lg_u32 s4, 0
	s_cbranch_scc1 .Lattn_loop
	v_cvt_pk_bf16_f32 v152, v64, v65
	v_cvt_pk_bf16_f32 v153, v66, v67
	v_cvt_pk_bf16_f32 v154, v68, v69
	v_cvt_pk_bf16_f32 v155, v70, v71
	v_cvt_pk_bf16_f32 v156, v72, v73
	v_cvt_pk_bf16_f32 v157, v74, v75
	v_cvt_pk_bf16_f32 v158, v76, v77
	v_cvt_pk_bf16_f32 v159, v78, v79
	v_add_f32_e32 v239, v64, v65
	v_add_f32_e32 v239, v66, v239
	v_add_f32_e32 v239, v67, v239
	v_add_f32_e32 v239, v68, v239
	v_add_f32_e32 v239, v69, v239
	v_add_f32_e32 v239, v70, v239
	v_add_f32_e32 v239, v71, v239
	v_add_f32_e32 v239, v72, v239
	v_add_f32_e32 v239, v73, v239
	v_add_f32_e32 v239, v74, v239
	v_add_f32_e32 v239, v75, v239
	v_add_f32_e32 v239, v76, v239
	v_add_f32_e32 v239, v77, v239
	v_add_f32_e32 v239, v78, v239
	v_add_f32_e32 v239, v79, v239
	v_add_f32_e32 v197, v239, v197
	s_waitcnt lgkmcnt(0)
	ds_read_b64_tr_b16 v[222:223], v188
	ds_read_b64_tr_b16 v[224:225], v188 offset:2048
	ds_read_b64_tr_b16 v[226:227], v188 offset:512
	ds_read_b64_tr_b16 v[228:229], v188 offset:2560
	ds_read_b64_tr_b16 v[230:231], v188 offset:1024
	ds_read_b64_tr_b16 v[232:233], v188 offset:3072
	ds_read_b64_tr_b16 v[234:235], v188 offset:1536
	ds_read_b64_tr_b16 v[236:237], v188 offset:3584
	ds_read_b64_tr_b16 v[240:241], v188 offset:4096
	ds_read_b64_tr_b16 v[242:243], v188 offset:6144
	ds_read_b64_tr_b16 v[180:181], v188 offset:4608
	ds_read_b64_tr_b16 v[182:183], v188 offset:6656
	s_waitcnt lgkmcnt(6)
	v_mfma_f32_32x32x16_bf16 v[0:15], v[140:143], v[222:225], v[0:15]
	ds_read_b64_tr_b16 v[222:223], v188 offset:5120
	ds_read_b64_tr_b16 v[224:225], v188 offset:7168
	v_mfma_f32_32x32x16_bf16 v[16:31], v[140:143], v[226:229], v[16:31]
	ds_read_b64_tr_b16 v[226:227], v188 offset:5632
	ds_read_b64_tr_b16 v[228:229], v188 offset:7680
	v_mfma_f32_32x32x16_bf16 v[32:47], v[140:143], v[230:233], v[32:47]
	ds_read_b64_tr_b16 v[230:231], v188 offset:8192
	ds_read_b64_tr_b16 v[232:233], v188 offset:10240
	s_waitcnt lgkmcnt(6)
	v_mfma_f32_32x32x16_bf16 v[48:63], v[140:143], v[234:237], v[48:63]
	ds_read_b64_tr_b16 v[234:235], v188 offset:8704
	ds_read_b64_tr_b16 v[236:237], v188 offset:10752
	v_mfma_f32_32x32x16_bf16 v[0:15], v[144:147], v[240:243], v[0:15]
	ds_read_b64_tr_b16 v[240:241], v188 offset:9216
	ds_read_b64_tr_b16 v[242:243], v188 offset:11264
	v_mfma_f32_32x32x16_bf16 v[16:31], v[144:147], v[180:183], v[16:31]
	ds_read_b64_tr_b16 v[180:181], v188 offset:9728
	ds_read_b64_tr_b16 v[182:183], v188 offset:11776
	s_waitcnt lgkmcnt(6)
	v_mfma_f32_32x32x16_bf16 v[32:47], v[144:147], v[222:225], v[32:47]
	ds_read_b64_tr_b16 v[222:223], v188 offset:12288
	ds_read_b64_tr_b16 v[224:225], v188 offset:14336
	v_mfma_f32_32x32x16_bf16 v[48:63], v[144:147], v[226:229], v[48:63]
	ds_read_b64_tr_b16 v[226:227], v188 offset:12800
	ds_read_b64_tr_b16 v[228:229], v188 offset:14848
	v_mfma_f32_32x32x16_bf16 v[0:15], v[152:155], v[230:233], v[0:15]
	ds_read_b64_tr_b16 v[230:231], v188 offset:13312
	ds_read_b64_tr_b16 v[232:233], v188 offset:15360
	s_waitcnt lgkmcnt(6)
	v_mfma_f32_32x32x16_bf16 v[16:31], v[152:155], v[234:237], v[16:31]
	ds_read_b64_tr_b16 v[234:235], v188 offset:13824
	ds_read_b64_tr_b16 v[236:237], v188 offset:15872
	v_mfma_f32_32x32x16_bf16 v[32:47], v[152:155], v[240:243], v[32:47]
	v_mfma_f32_32x32x16_bf16 v[48:63], v[152:155], v[180:183], v[48:63]
	s_waitcnt lgkmcnt(2)
	v_mfma_f32_32x32x16_bf16 v[0:15], v[156:159], v[222:225], v[0:15]
	v_mfma_f32_32x32x16_bf16 v[16:31], v[156:159], v[226:229], v[16:31]
	v_mfma_f32_32x32x16_bf16 v[32:47], v[156:159], v[230:233], v[32:47]
	s_waitcnt lgkmcnt(0)
	v_mfma_f32_32x32x16_bf16 v[48:63], v[156:159], v[234:237], v[48:63]
	s_waitcnt vmcnt(0)
	v_mov_b32_e32 v64, v197
	v_mov_b32_e32 v65, v197
	v_and_b32_e32 v80, 0x3fffffc0, v195
	s_mov_b32 s0, 0x10000
	v_permlane32_swap_b32_e32 v64, v65
	v_lshl_add_u32 v80, v80, 2, s0
	v_cmp_gt_u32_e32 vcc, 32, v179
	v_add_f32_e32 v64, v64, v65
	v_mov_b32_e32 v66, v191
	v_add_f32_e32 v64, 0xc2400000, v64
	s_nop 3
	s_and_saveexec_b64 s[0:1], vcc
	s_cbranch_execz .LBB0_439
	v_lshl_add_u32 v65, v66, 2, v80
	ds_write_b32 v65, v64
	s_branch .LBB0_439
